# in-proj epilogue tail: the eight LDS reads of the transposed tile issued together, stores follow with counted lgkmcnt waits
# speedup vs baseline: 1.0335x; 1.0032x over previous
.LBB0_183:
	v_cvt_pk_bf16_f32 v4, v20, v21
	v_cvt_pk_bf16_f32 v5, v22, v23
	ds_write_b64 v60, v[4:5] offset:13152
	s_waitcnt lgkmcnt(0)
	s_barrier
	ds_read_b128 v[4:7], v134
	ds_read_b128 v[12:15], v136
	ds_read_b128 v[16:19], v138
	ds_read_b128 v[20:23], v140
	ds_read_b128 v[24:27], v142
	ds_read_b128 v[28:31], v144
	ds_read_b128 v[32:35], v146
	ds_read_b128 v[36:39], v148
	s_lshl_b32 s22, s22, 1
	v_lshl_add_u64 v[8:9], v[150:151], 0, s[22:23]
	v_add_u32_e32 v2, s58, v181
	v_mad_i64_i32 v[10:11], s[0:1], v2, s48, v[8:9]
	s_waitcnt lgkmcnt(7)
	global_store_dwordx4 v[10:11], v[4:7], off
	v_add_u32_e32 v2, s58, v182
	v_mad_i64_i32 v[10:11], s[0:1], v2, s48, v[8:9]
	v_add_u32_e32 v2, s58, v137
	s_waitcnt lgkmcnt(6)
	global_store_dwordx4 v[10:11], v[12:15], off
	v_mad_i64_i32 v[10:11], s[0:1], v2, s48, v[8:9]
	v_add_u32_e32 v2, s58, v139
	s_waitcnt lgkmcnt(5)
	global_store_dwordx4 v[10:11], v[16:19], off
	v_mad_i64_i32 v[10:11], s[0:1], v2, s48, v[8:9]
	v_add_u32_e32 v2, s58, v141
	s_waitcnt lgkmcnt(4)
	global_store_dwordx4 v[10:11], v[20:23], off
	v_mad_i64_i32 v[10:11], s[0:1], v2, s48, v[8:9]
	v_add_u32_e32 v2, s58, v143
	s_waitcnt lgkmcnt(3)
	global_store_dwordx4 v[10:11], v[24:27], off
	v_mad_i64_i32 v[10:11], s[0:1], v2, s48, v[8:9]
	v_add_u32_e32 v2, s58, v145
	s_waitcnt lgkmcnt(2)
	global_store_dwordx4 v[10:11], v[28:31], off
	v_mad_i64_i32 v[10:11], s[0:1], v2, s48, v[8:9]
	v_add_u32_e32 v2, s58, v147
	v_mad_i64_i32 v[8:9], s[0:1], v2, s48, v[8:9]
	s_waitcnt lgkmcnt(1)
	global_store_dwordx4 v[10:11], v[32:35], off
	v_readlane_b32 s0, v252, 0
	s_add_i32 s36, s36, s0
	s_cmpk_lt_u32 s36, 0x3b8
	s_waitcnt lgkmcnt(0)
	global_store_dwordx4 v[8:9], v[36:39], off
	s_barrier
	s_cbranch_scc0 .LBB0_487
